# gMLP LayerNorm bf16 loads issued in one batch per 4-token cluster; attention steps: counted lgkmcnt waits so the first QK MFMAs do not wait for the V fragment reads
# speedup vs baseline: 1.0230x; 1.0026x over previous
.LBB0_276:
	s_and_b64 vcc, exec, s[38:39]
	v_exp_f32_e32 v112, v112
	v_exp_f32_e32 v113, v113
	v_exp_f32_e32 v114, v114
	v_exp_f32_e32 v115, v115
	v_add_f32_e32 v80, v189, v112
	v_add_f32_e32 v81, v188, v113
	v_exp_f32_e32 v116, v116
	v_exp_f32_e32 v117, v117
	v_exp_f32_e32 v118, v118
	v_exp_f32_e32 v119, v119
	v_add_f32_e32 v80, v114, v80
	v_add_f32_e32 v81, v115, v81
	v_cvt_pk_bf16_f32 v188, v112, v113
	v_add_f32_e32 v80, v116, v80
	v_add_f32_e32 v81, v117, v81
	v_cvt_pk_bf16_f32 v189, v114, v115
	v_add_f32_e32 v100, v118, v80
	v_add_f32_e32 v101, v119, v81
	v_cvt_pk_bf16_f32 v190, v116, v117
	v_cvt_pk_bf16_f32 v191, v118, v119
	v_exp_f32_e32 v120, v120
	v_exp_f32_e32 v121, v121
	s_waitcnt lgkmcnt(6)
	v_mfma_f32_32x32x16_bf16 v[80:95], v[96:99], v[144:147], v[64:79]
	v_add_u32_e32 v96, v237, v226
	v_add_f32_e32 v194, v120, v100
	v_add_f32_e32 v195, v121, v101
	ds_read_b128 v[238:241], v96 offset:32768
	ds_read_b128 v[242:245], v96 offset:40960
	v_exp_f32_e32 v122, v122
	v_exp_f32_e32 v123, v123
	v_mfma_f32_32x32x16_bf16 v[96:111], v[184:187], v[144:147], v[64:79]
	v_add_u32_e32 v186, v237, v227
	v_add_f32_e32 v184, v122, v194
	v_add_f32_e32 v185, v123, v195
	ds_read_b128 v[246:249], v186 offset:32768
	ds_read_b128 v[250:253], v186 offset:40960
	s_waitcnt lgkmcnt(8)
	v_mfma_f32_32x32x16_bf16 v[80:95], v[180:183], v[148:151], v[80:95]
	v_exp_f32_e32 v124, v124
	v_exp_f32_e32 v125, v125
	v_add_f32_e32 v180, v124, v184
	v_add_f32_e32 v181, v125, v185
	s_cbranch_vccnz .Latt_dA0
	s_mov_b32 m0, s11
	s_nop 0
	global_load_lds_dwordx4 v206, s[98:99]
	v_add_u32_e32 v206, 0x10000, v206

.Latt_dA1:
	s_waitcnt lgkmcnt(2)
	v_mfma_f32_32x32x16_bf16 v[80:95], v[238:241], v[152:155], v[80:95]
	v_add_u32_e32 v180, v236, v230
	ds_read_b128 v[238:241], v180 offset:16384
	ds_read_b128 v[194:197], v180 offset:20480
	v_cvt_pk_bf16_f32 v176, v120, v121
	v_cvt_pk_bf16_f32 v177, v122, v123
	v_mfma_f32_32x32x16_bf16 v[96:111], v[242:245], v[152:155], v[96:111]
	ds_read_b128 v[184:187], v180 offset:24576
	ds_read_b128 v[180:183], v180 offset:28672
	v_cvt_pk_bf16_f32 v178, v124, v125
	v_cvt_pk_bf16_f32 v179, v126, v127
	s_waitcnt lgkmcnt(4)
	v_mfma_f32_32x32x16_bf16 v[80:95], v[246:249], v[156:159], v[80:95]
	v_exp_f32_e32 v128, v128
	v_exp_f32_e32 v129, v129
	v_add_f32_e32 v237, v128, v237
	v_add_f32_e32 v219, v129, v219
	s_cbranch_vccnz .Latt_dA2
	s_add_i32 m0, s11, 0x2000
	s_nop 0
	global_load_lds_dwordx4 v204, s[98:99]
	v_add_u32_e32 v204, 0x10000, v204

.LBB0_281:
	s_andn2_b64 vcc, exec, s[38:39]
	v_exp_f32_e32 v80, v80
	v_exp_f32_e32 v81, v81
	v_exp_f32_e32 v82, v82
	v_exp_f32_e32 v83, v83
	v_add_f32_e32 v112, v189, v80
	v_add_f32_e32 v113, v188, v81
	v_exp_f32_e32 v84, v84
	v_exp_f32_e32 v85, v85
	v_exp_f32_e32 v86, v86
	v_exp_f32_e32 v87, v87
	v_add_f32_e32 v112, v82, v112
	v_add_f32_e32 v113, v83, v113
	v_cvt_pk_bf16_f32 v188, v80, v81
	v_add_f32_e32 v112, v84, v112
	v_add_f32_e32 v113, v85, v113
	v_cvt_pk_bf16_f32 v189, v82, v83
	v_add_f32_e32 v132, v86, v112
	v_add_f32_e32 v133, v87, v113
	v_cvt_pk_bf16_f32 v190, v84, v85
	v_cvt_pk_bf16_f32 v191, v86, v87
	v_exp_f32_e32 v88, v88
	v_exp_f32_e32 v89, v89
	s_waitcnt lgkmcnt(6)
	v_mfma_f32_32x32x16_bf16 v[112:127], v[128:131], v[144:147], v[64:79]
	v_add_u32_e32 v128, v209, v226
	v_add_f32_e32 v214, v88, v132
	v_add_f32_e32 v215, v89, v133
	ds_read_b128 v[194:197], v128
	ds_read_b128 v[210:213], v128 offset:8192
	v_exp_f32_e32 v90, v90
	v_exp_f32_e32 v91, v91
	v_mfma_f32_32x32x16_bf16 v[128:143], v[184:187], v[144:147], v[64:79]
	v_add_u32_e32 v186, v209, v227
	v_add_f32_e32 v184, v90, v214
	v_add_f32_e32 v185, v91, v215
	ds_read_b128 v[236:239], v186
	ds_read_b128 v[240:243], v186 offset:8192
	s_waitcnt lgkmcnt(8)
	v_mfma_f32_32x32x16_bf16 v[112:127], v[180:183], v[148:151], v[112:127]
	v_exp_f32_e32 v92, v92
	v_exp_f32_e32 v93, v93
	v_add_f32_e32 v180, v92, v184
	v_add_f32_e32 v181, v93, v185
	s_cbranch_vccnz .Latt_dB0
	s_mov_b32 m0, s10
	s_nop 0
	global_load_lds_dwordx4 v206, s[98:99]
	v_add_u32_e32 v206, 0x10000, v206

.Latt_dB1:
	s_waitcnt lgkmcnt(2)
	v_mfma_f32_32x32x16_bf16 v[112:127], v[194:197], v[152:155], v[112:127]
	v_add_u32_e32 v180, v208, v230
	ds_read_b128 v[194:197], v180 offset:49152
	ds_read_b128 v[244:247], v180 offset:53248
	v_cvt_pk_bf16_f32 v176, v88, v89
	v_cvt_pk_bf16_f32 v177, v90, v91
	v_mfma_f32_32x32x16_bf16 v[128:143], v[210:213], v[152:155], v[128:143]
	ds_read_b128 v[184:187], v180 offset:57344
	ds_read_b128 v[180:183], v180 offset:61440
	v_cvt_pk_bf16_f32 v178, v92, v93
	v_cvt_pk_bf16_f32 v179, v94, v95
	s_waitcnt lgkmcnt(4)
	v_mfma_f32_32x32x16_bf16 v[112:127], v[236:239], v[156:159], v[112:127]
	v_exp_f32_e32 v96, v96
	v_exp_f32_e32 v97, v97
	v_add_f32_e32 v209, v96, v209
	v_add_f32_e32 v210, v97, v214
	s_cbranch_vccnz .Latt_dB2
	s_add_i32 m0, s10, 0x2000
	s_nop 0
	global_load_lds_dwordx4 v204, s[98:99]
	v_add_u32_e32 v204, 0x10000, v204

; __device__ __forceinline__ void gmlp_unit(LAS unsigned char* lds, const bf16_t* U, const bf16_t* VG, const bf16_t* Wg, const float* lng, const float* lnb, const float* bias, bf16_t* Y, int blk, int wid0) {
;     ...
;         for (int u = 0; u < 8; ++u) { const bf16_t* vp = VG + (tok0 + wid * 16 + t8 + u) * 512 + lane;
; #pragma unroll
;             for (int i = 0; i < 8; ++i) v[u][i] = bf2f(vp[64 * i]); }
; #pragma unroll
;         for (int u = 0; u < 8; ++u) { const int s = wid * 16 + t8 + u; float sum = 0.f;
; #pragma unroll
;             for (int i = 0; i < 8; ++i) sum += v[u][i];
;             const float mean = wave_sum(sum, lane) * (1.0f / 512.0f); float q = 0.f;
.LBB0_292:
	s_or_b32 s82, s7, s22
	s_or_b32 s22, s22, s6
	v_cndmask_b32_e64 v74, 0, 1, s[40:41]
	s_lshl_b64 s[10:11], s[82:83], 10
	s_lshr_b32 s22, s22, 3
	v_cmp_ne_u32_e64 s[38:39], 1, v74
	v_lshl_add_u64 v[74:75], v[40:41], 0, s[10:11]
	v_xor_b32_e32 v76, s22, v186
	v_lshl_add_u32 v106, v76, 4, v95
	flat_load_ushort v78, v[74:75]
	flat_load_ushort v79, v[74:75] offset:1024
	flat_load_ushort v76, v[74:75] offset:2048
	flat_load_ushort v77, v[74:75] offset:3072
	flat_load_ushort v82, v[74:75] offset:128
	flat_load_ushort v83, v[74:75] offset:1152
	flat_load_ushort v80, v[74:75] offset:2176
	flat_load_ushort v81, v[74:75] offset:3200
	flat_load_ushort v90, v[74:75] offset:256
	flat_load_ushort v91, v[74:75] offset:1280
	flat_load_ushort v88, v[74:75] offset:2304
	flat_load_ushort v89, v[74:75] offset:3328
	flat_load_ushort v107, v[74:75] offset:384
	flat_load_ushort v108, v[74:75] offset:1408
	flat_load_ushort v92, v[74:75] offset:2432
	flat_load_ushort v93, v[74:75] offset:3456
	flat_load_ushort v236, v[74:75] offset:512
	flat_load_ushort v112, v[74:75] offset:1536
	flat_load_ushort v110, v[74:75] offset:2560
	flat_load_ushort v111, v[74:75] offset:3584
	flat_load_ushort v237, v[74:75] offset:640
	flat_load_ushort v116, v[74:75] offset:1664
	flat_load_ushort v114, v[74:75] offset:2688
	flat_load_ushort v115, v[74:75] offset:3712
	flat_load_ushort v238, v[74:75] offset:768
	flat_load_ushort v120, v[74:75] offset:1792
	flat_load_ushort v118, v[74:75] offset:2816
	flat_load_ushort v119, v[74:75] offset:3840
	flat_load_ushort v239, v[74:75] offset:896
	flat_load_ushort v124, v[74:75] offset:1920
	flat_load_ushort v122, v[74:75] offset:2944
	flat_load_ushort v123, v[74:75] offset:3968
	v_add_u32_e32 v105, 0x10000, v106
	v_add_u32_e32 v104, 0x14000, v106
	v_add_u32_e32 v103, 0x18000, v106
	v_add_u32_e32 v102, 0x1c000, v106
	s_mov_b32 s22, 8
	s_waitcnt vmcnt(0) lgkmcnt(0)
	v_lshlrev_b32_e32 v78, 16, v78
	v_lshlrev_b32_e32 v79, 16, v79
	v_lshlrev_b32_e32 v83, 16, v83
	v_lshlrev_b32_e32 v82, 16, v82
	v_lshlrev_b32_e32 v109, 16, v108
	v_lshlrev_b32_e32 v108, 16, v107
	s_nop 0
	s_nop 0
	s_nop 0
	s_nop 0
	v_pk_add_f32 v[84:85], v[78:79], 0 op_sel_hi:[1,0]
	v_lshlrev_b32_e32 v91, 16, v91
	v_pk_add_f32 v[84:85], v[84:85], v[82:83]
	v_lshlrev_b32_e32 v90, 16, v90
	v_pk_add_f32 v[84:85], v[84:85], v[90:91]
	v_lshlrev_b32_e32 v77, 16, v77
	v_pk_add_f32 v[84:85], v[84:85], v[108:109]
	v_lshlrev_b32_e32 v76, 16, v76
	v_lshlrev_b32_e32 v81, 16, v81
	v_lshlrev_b32_e32 v80, 16, v80
	v_pk_add_f32 v[86:87], v[76:77], 0 op_sel_hi:[1,0]
	v_lshlrev_b32_e32 v89, 16, v89
	v_pk_add_f32 v[86:87], v[86:87], v[80:81]
	v_lshlrev_b32_e32 v88, 16, v88
	v_lshlrev_b32_e32 v93, 16, v93
	v_lshlrev_b32_e32 v92, 16, v92
	v_pk_add_f32 v[86:87], v[86:87], v[88:89]
	s_nop 0
	v_lshlrev_b32_e32 v113, 16, v112
	v_lshlrev_b32_e32 v112, 16, v236
	s_nop 0
	s_nop 0
	s_nop 0
	s_nop 0
	v_pk_add_f32 v[84:85], v[84:85], v[112:113]
	v_lshlrev_b32_e32 v111, 16, v111
	v_lshlrev_b32_e32 v110, 16, v110
	v_pk_add_f32 v[86:87], v[86:87], v[92:93]
	s_nop 0
	v_lshlrev_b32_e32 v117, 16, v116
	v_lshlrev_b32_e32 v116, 16, v237
	s_nop 0
	s_nop 0
	s_nop 0
	s_nop 0
	v_pk_add_f32 v[84:85], v[84:85], v[116:117]
	v_lshlrev_b32_e32 v115, 16, v115
	v_lshlrev_b32_e32 v114, 16, v114
	v_pk_add_f32 v[86:87], v[86:87], v[110:111]
	s_nop 0
	v_lshlrev_b32_e32 v121, 16, v120
	v_lshlrev_b32_e32 v120, 16, v238
	s_nop 0
	s_nop 0
	s_nop 0
	s_nop 0
	v_pk_add_f32 v[84:85], v[84:85], v[120:121]
	v_lshlrev_b32_e32 v119, 16, v119
	v_lshlrev_b32_e32 v118, 16, v118
	v_pk_add_f32 v[86:87], v[86:87], v[114:115]
	s_nop 0
	v_lshlrev_b32_e32 v125, 16, v124
	v_lshlrev_b32_e32 v124, 16, v239
	v_pk_add_f32 v[84:85], v[84:85], v[124:125]
	ds_bpermute_b32 v126, v96, v84
	ds_bpermute_b32 v127, v96, v85
	v_lshlrev_b32_e32 v123, 16, v123
	v_lshlrev_b32_e32 v122, 16, v122
	v_pk_add_f32 v[86:87], v[86:87], v[118:119]
	s_waitcnt lgkmcnt(0)
	v_pk_add_f32 v[84:85], v[84:85], v[126:127]
	v_pk_add_f32 v[86:87], v[86:87], v[122:123]
	ds_bpermute_b32 v188, v96, v86
	ds_bpermute_b32 v189, v96, v87
	ds_bpermute_b32 v126, v97, v84
	ds_bpermute_b32 v127, v97, v85
	s_waitcnt lgkmcnt(2)
	v_pk_add_f32 v[86:87], v[86:87], v[188:189]
	ds_bpermute_b32 v188, v97, v86
	s_waitcnt lgkmcnt(1)
	v_pk_add_f32 v[84:85], v[84:85], v[126:127]
	ds_bpermute_b32 v189, v97, v87
	ds_bpermute_b32 v126, v98, v84
	ds_bpermute_b32 v127, v98, v85
	s_waitcnt lgkmcnt(2)
	v_pk_add_f32 v[86:87], v[86:87], v[188:189]
	ds_bpermute_b32 v188, v98, v86
	s_waitcnt lgkmcnt(1)
	v_pk_add_f32 v[84:85], v[84:85], v[126:127]
	ds_bpermute_b32 v189, v98, v87
	ds_bpermute_b32 v126, v99, v84
	ds_bpermute_b32 v127, v99, v85
	s_waitcnt lgkmcnt(2)
	v_pk_add_f32 v[86:87], v[86:87], v[188:189]
	ds_bpermute_b32 v188, v99, v86
	s_waitcnt lgkmcnt(1)
	v_pk_add_f32 v[84:85], v[84:85], v[126:127]
	ds_bpermute_b32 v189, v99, v87
	ds_bpermute_b32 v126, v100, v84
	ds_bpermute_b32 v127, v100, v85
	s_waitcnt lgkmcnt(2)
	v_pk_add_f32 v[86:87], v[86:87], v[188:189]
	ds_bpermute_b32 v188, v100, v86
	s_waitcnt lgkmcnt(1)
	v_pk_add_f32 v[84:85], v[84:85], v[126:127]
	ds_bpermute_b32 v189, v100, v87
	ds_bpermute_b32 v126, v101, v84
	ds_bpermute_b32 v127, v101, v85
	s_waitcnt lgkmcnt(2)
	v_pk_add_f32 v[86:87], v[86:87], v[188:189]
	ds_bpermute_b32 v188, v101, v86
	ds_bpermute_b32 v189, v101, v87
	s_waitcnt lgkmcnt(2)
	v_pk_add_f32 v[126:127], v[84:85], v[126:127]
	s_waitcnt lgkmcnt(0)
; __device__ __forceinline__ void gmlp_unit(LAS unsigned char* lds, const bf16_t* U, const bf16_t* VG, const bf16_t* Wg, const float* lng, const float* lnb, const float* bias, bf16_t* Y, int blk, int wid0) {
;     ...
;             const float mean = wave_sum(sum, lane) * (1.0f / 512.0f); float q = 0.f;
; #pragma unroll
;             for (int i = 0; i < 8; ++i) { v[u][i] -= mean; q += v[u][i] * v[u][i]; }
;             const float rstd = 1.0f / sqrtf(wave_sum(q, lane) * (1.0f / 512.0f) + EPS);
	v_pk_add_f32 v[188:189], v[86:87], v[188:189]
	v_pk_fma_f32 v[204:205], v[126:127], s[16:17], v[82:83] op_sel_hi:[1,0,1] neg_lo:[1,0,0] neg_hi:[1,0,0]
	v_pk_fma_f32 v[194:195], v[126:127], s[16:17], v[78:79] op_sel_hi:[1,0,1] neg_lo:[1,0,0] neg_hi:[1,0,0]
	v_mul_f32_e32 v107, v204, v204
	v_fmac_f32_e32 v107, v194, v194
	v_pk_fma_f32 v[208:209], v[126:127], s[16:17], v[90:91] op_sel_hi:[1,0,1] neg_lo:[1,0,0] neg_hi:[1,0,0]
	v_pk_fma_f32 v[108:109], v[126:127], s[16:17], v[108:109] op_sel_hi:[1,0,1] neg_lo:[1,0,0] neg_hi:[1,0,0]
	v_fmac_f32_e32 v107, v208, v208
	v_fmac_f32_e32 v107, v108, v108
	v_pk_fma_f32 v[90:91], v[126:127], s[16:17], v[112:113] op_sel_hi:[1,0,1] neg_lo:[1,0,0] neg_hi:[1,0,0]
	v_pk_fma_f32 v[82:83], v[126:127], s[16:17], v[120:121] op_sel_hi:[1,0,1] neg_lo:[1,0,0] neg_hi:[1,0,0]
	v_pk_fma_f32 v[78:79], v[126:127], s[16:17], v[124:125] op_sel_hi:[1,0,1] neg_lo:[1,0,0] neg_hi:[1,0,0]
	v_pk_fma_f32 v[206:207], v[188:189], s[16:17], v[88:89] op_sel_hi:[1,0,1] neg_lo:[1,0,0] neg_hi:[1,0,0]
	v_pk_fma_f32 v[88:89], v[188:189], s[16:17], v[110:111] op_sel_hi:[1,0,1] neg_lo:[1,0,0] neg_hi:[1,0,0]
	v_fmac_f32_e32 v107, v90, v90
	v_pk_fma_f32 v[86:87], v[126:127], s[16:17], v[116:117] op_sel_hi:[1,0,1] neg_lo:[1,0,0] neg_hi:[1,0,0]
	v_mov_b32_e32 v110, v78
	v_mov_b32_e32 v111, v82
	v_fmac_f32_e32 v107, v86, v86
	v_pk_mul_f32 v[110:111], v[110:111], v[110:111]
	v_pk_fma_f32 v[196:197], v[188:189], s[16:17], v[80:81] op_sel_hi:[1,0,1] neg_lo:[1,0,0] neg_hi:[1,0,0]
	v_add_f32_e32 v107, v111, v107
	v_add_f32_e32 v107, v110, v107
	ds_bpermute_b32 v110, v96, v107
	v_pk_fma_f32 v[190:191], v[188:189], s[16:17], v[76:77] op_sel_hi:[1,0,1] neg_lo:[1,0,0] neg_hi:[1,0,0]
	v_pk_fma_f32 v[92:93], v[188:189], s[16:17], v[92:93] op_sel_hi:[1,0,1] neg_lo:[1,0,0] neg_hi:[1,0,0]
	v_pk_fma_f32 v[80:81], v[188:189], s[16:17], v[118:119] op_sel_hi:[1,0,1] neg_lo:[1,0,0] neg_hi:[1,0,0]
	v_pk_fma_f32 v[76:77], v[188:189], s[16:17], v[122:123] op_sel_hi:[1,0,1] neg_lo:[1,0,0] neg_hi:[1,0,0]
	s_waitcnt lgkmcnt(0)
	v_add_f32_e32 v107, v107, v110
	ds_bpermute_b32 v110, v97, v107
	v_pk_fma_f32 v[84:85], v[188:189], s[16:17], v[114:115] op_sel_hi:[1,0,1] neg_lo:[1,0,0] neg_hi:[1,0,0]
	s_waitcnt lgkmcnt(0)
	v_add_f32_e32 v107, v107, v110
	ds_bpermute_b32 v110, v98, v107
	s_waitcnt lgkmcnt(0)
	v_add_f32_e32 v107, v107, v110
	ds_bpermute_b32 v110, v99, v107
	s_waitcnt lgkmcnt(0)
	v_add_f32_e32 v107, v107, v110
	ds_bpermute_b32 v110, v100, v107
	s_waitcnt lgkmcnt(0)
	v_add_f32_e32 v107, v107, v110
	ds_bpermute_b32 v110, v101, v107
	s_waitcnt lgkmcnt(0)
	v_add_f32_e32 v107, v107, v110
	v_fmamk_f32 v107, v107, 0x3b000000, v217
	v_cmp_gt_f32_e32 vcc, s59, v107
	v_mul_f32_e32 v110, 0x4f800000, v107
	s_nop 0
	v_cndmask_b32_e32 v107, v107, v110, vcc
	v_sqrt_f32_e32 v110, v107
	s_nop 0
	v_add_u32_e32 v111, -1, v110
	v_fma_f32 v112, -v111, v110, v107
	v_cmp_ge_f32_e64 s[40:41], 0, v112
	v_add_u32_e32 v112, 1, v110
	s_nop 0
	v_cndmask_b32_e64 v111, v110, v111, s[40:41]
	v_fma_f32 v110, -v112, v110, v107
	v_cmp_lt_f32_e64 s[40:41], 0, v110
	s_nop 1
	v_cndmask_b32_e64 v110, v111, v112, s[40:41]
	v_mul_f32_e32 v112, v205, v205
	v_fmac_f32_e32 v112, v195, v195
	v_mul_f32_e32 v111, 0x37800000, v110
	v_fmac_f32_e32 v112, v209, v209
	v_cndmask_b32_e32 v110, v110, v111, vcc
	v_cmp_class_f32_e32 vcc, v107, v218
	v_fmac_f32_e32 v112, v109, v109
	v_fmac_f32_e32 v112, v91, v91
	v_cndmask_b32_e32 v107, v110, v107, vcc
	v_mov_b32_e32 v110, v79
	v_mov_b32_e32 v111, v83
	v_fmac_f32_e32 v112, v87, v87
	v_pk_mul_f32 v[110:111], v[110:111], v[110:111]
	s_nop 0
	v_add_f32_e32 v111, v111, v112
	v_add_f32_e32 v110, v110, v111
	ds_bpermute_b32 v111, v96, v110
	s_waitcnt lgkmcnt(0)
	v_add_f32_e32 v110, v110, v111
	ds_bpermute_b32 v111, v97, v110
	s_waitcnt lgkmcnt(0)
	v_add_f32_e32 v110, v110, v111
	ds_bpermute_b32 v111, v98, v110
	s_waitcnt lgkmcnt(0)
	v_add_f32_e32 v110, v110, v111
	ds_bpermute_b32 v111, v99, v110
	s_waitcnt lgkmcnt(0)
	v_add_f32_e32 v110, v110, v111
	ds_bpermute_b32 v111, v100, v110
	s_waitcnt lgkmcnt(0)
	v_add_f32_e32 v110, v110, v111
	ds_bpermute_b32 v111, v101, v110
	s_waitcnt lgkmcnt(0)
	v_add_f32_e32 v110, v110, v111
	v_fmamk_f32 v110, v110, 0x3b000000, v217
	v_cmp_gt_f32_e32 vcc, s59, v110
	v_mul_f32_e32 v111, 0x4f800000, v110
	s_nop 0
	v_cndmask_b32_e32 v110, v110, v111, vcc
	v_sqrt_f32_e32 v111, v110
	s_nop 0
	v_add_u32_e32 v112, -1, v111
	v_fma_f32 v113, -v112, v111, v110
	v_cmp_ge_f32_e64 s[40:41], 0, v113
	v_add_u32_e32 v113, 1, v111
	s_nop 0
	v_cndmask_b32_e64 v112, v111, v112, s[40:41]
	v_fma_f32 v111, -v113, v111, v110
	v_cmp_lt_f32_e64 s[40:41], 0, v111
	s_nop 1
	v_cndmask_b32_e64 v111, v112, v113, s[40:41]
	v_mul_f32_e32 v113, v196, v196
	v_fmac_f32_e32 v113, v190, v190
	v_mul_f32_e32 v112, 0x37800000, v111
	v_fmac_f32_e32 v113, v206, v206
	v_cndmask_b32_e32 v111, v111, v112, vcc
	v_cmp_class_f32_e32 vcc, v110, v218
	v_fmac_f32_e32 v113, v92, v92
	v_fmac_f32_e32 v113, v88, v88
	v_cndmask_b32_e32 v112, v111, v110, vcc
	v_mov_b32_e32 v110, v76
	v_mov_b32_e32 v111, v80
	v_fmac_f32_e32 v113, v84, v84
	v_pk_mul_f32 v[110:111], v[110:111], v[110:111]
	s_nop 0
	v_add_f32_e32 v111, v111, v113
	v_add_f32_e32 v110, v110, v111
	ds_bpermute_b32 v111, v96, v110
	s_waitcnt lgkmcnt(0)
	v_add_f32_e32 v110, v110, v111
	ds_bpermute_b32 v111, v97, v110
	s_waitcnt lgkmcnt(0)
	v_add_f32_e32 v110, v110, v111
	ds_bpermute_b32 v111, v98, v110
	s_waitcnt lgkmcnt(0)
	v_add_f32_e32 v110, v110, v111
	ds_bpermute_b32 v111, v99, v110
	s_waitcnt lgkmcnt(0)
	v_add_f32_e32 v110, v110, v111
	ds_bpermute_b32 v111, v100, v110
	s_waitcnt lgkmcnt(0)
; #define LAS __attribute__((address_space(3)))
; __device__ __forceinline__ unsigned f2bf(float f) { unsigned u = __builtin_bit_cast(unsigned, f); return (u + 0x7fffu + ((u >> 16) & 1u)) >> 16; }
; __device__ __forceinline__ void gmlp_unit(LAS unsigned char* lds, const bf16_t* U, const bf16_t* VG, const bf16_t* Wg, const float* lng, const float* lnb, const float* bias, bf16_t* Y, int blk, int wid0) {
;     ...
;             for (int i = 0; i < 8; ++i) { v[u][i] -= mean; q += v[u][i] * v[u][i]; }
;             const float rstd = 1.0f / sqrtf(wave_sum(q, lane) * (1.0f / 512.0f) + EPS);
; #pragma unroll
;             for (int i = 0; i < 8; ++i) { const int c = lane + 64 * i; const float y = v[u][i] * rstd * lg[i] + lb[i];
;                 *(LAS bf16_t*)(lds + c * 256 + ((((s >> 3) ^ (c & 15))) << 4) + (s & 7) * 2) = (bf16_t)f2bf(y); } }
	v_add_f32_e32 v110, v110, v111
	ds_bpermute_b32 v111, v101, v110
	s_waitcnt lgkmcnt(0)
	v_add_f32_e32 v110, v110, v111
	v_fmamk_f32 v110, v110, 0x3b000000, v217
	v_cmp_gt_f32_e32 vcc, s59, v110
	v_mul_f32_e32 v111, 0x4f800000, v110
	s_nop 0
	v_cndmask_b32_e32 v110, v110, v111, vcc
	v_sqrt_f32_e32 v111, v110
	s_nop 0
	v_add_u32_e32 v113, -1, v111
	v_fma_f32 v114, -v113, v111, v110
	v_cmp_ge_f32_e64 s[40:41], 0, v114
	v_add_u32_e32 v114, 1, v111
	s_nop 0
	v_cndmask_b32_e64 v113, v111, v113, s[40:41]
	v_fma_f32 v111, -v114, v111, v110
	v_cmp_lt_f32_e64 s[40:41], 0, v111
	s_nop 1
	v_cndmask_b32_e64 v111, v113, v114, s[40:41]
	v_mul_f32_e32 v114, v197, v197
	v_fmac_f32_e32 v114, v191, v191
	v_mul_f32_e32 v113, 0x37800000, v111
	v_fmac_f32_e32 v114, v207, v207
	v_cndmask_b32_e32 v111, v111, v113, vcc
	v_cmp_class_f32_e32 vcc, v110, v218
	v_fmac_f32_e32 v114, v93, v93
	v_fmac_f32_e32 v114, v89, v89
	v_cndmask_b32_e32 v113, v111, v110, vcc
	v_mov_b32_e32 v110, v77
	v_mov_b32_e32 v111, v81
	v_fmac_f32_e32 v114, v85, v85
	v_pk_mul_f32 v[110:111], v[110:111], v[110:111]
	s_nop 0
	v_add_f32_e32 v111, v111, v114
	v_add_f32_e32 v110, v110, v111
	ds_bpermute_b32 v111, v96, v110
	s_waitcnt lgkmcnt(0)
	v_add_f32_e32 v110, v110, v111
	ds_bpermute_b32 v111, v97, v110
	s_waitcnt lgkmcnt(0)
	v_add_f32_e32 v110, v110, v111
	ds_bpermute_b32 v111, v98, v110
	s_waitcnt lgkmcnt(0)
	v_add_f32_e32 v110, v110, v111
	ds_bpermute_b32 v111, v99, v110
	s_waitcnt lgkmcnt(0)
	v_add_f32_e32 v110, v110, v111
	ds_bpermute_b32 v111, v100, v110
	s_waitcnt lgkmcnt(0)
	v_add_f32_e32 v110, v110, v111
	ds_bpermute_b32 v111, v101, v110
	s_waitcnt lgkmcnt(0)
	v_add_f32_e32 v110, v110, v111
	v_fmamk_f32 v110, v110, 0x3b000000, v217
	v_cmp_gt_f32_e32 vcc, s59, v110
	v_mul_f32_e32 v111, 0x4f800000, v110
	s_nop 0
	v_cndmask_b32_e32 v110, v110, v111, vcc
	v_sqrt_f32_e32 v111, v110
	s_nop 0
	v_add_u32_e32 v114, -1, v111
	v_fma_f32 v115, -v114, v111, v110
	v_cmp_ge_f32_e64 s[40:41], 0, v115
	v_add_u32_e32 v115, 1, v111
	s_nop 0
	v_cndmask_b32_e64 v114, v111, v114, s[40:41]
	v_fma_f32 v111, -v115, v111, v110
	v_cmp_lt_f32_e64 s[40:41], 0, v111
	s_nop 1
	v_cndmask_b32_e64 v111, v114, v115, s[40:41]
	v_mul_f32_e32 v114, 0x37800000, v111
	v_cndmask_b32_e32 v111, v111, v114, vcc
	v_cmp_class_f32_e32 vcc, v110, v218
	s_nop 1
	v_cndmask_b32_e32 v110, v111, v110, vcc
	v_div_scale_f32 v111, s[10:11], v112, v112, 1.0
	v_rcp_f32_e32 v114, v111
	s_nop 0
	v_fma_f32 v115, -v111, v114, 1.0
	v_fmac_f32_e32 v114, v115, v114
	v_div_scale_f32 v115, vcc, 1.0, v112, 1.0
	v_mul_f32_e32 v116, v115, v114
	v_fma_f32 v117, -v111, v116, v115
	v_fmac_f32_e32 v116, v117, v114
	v_fma_f32 v111, -v111, v116, v115
	v_div_fmas_f32 v111, v111, v114, v116
	v_div_fixup_f32 v211, v111, v112, 1.0
	v_div_scale_f32 v111, s[10:11], v107, v107, 1.0
	v_rcp_f32_e32 v112, v111
	s_nop 0
	v_fma_f32 v114, -v111, v112, 1.0
	v_fmac_f32_e32 v112, v114, v112
	v_div_scale_f32 v114, vcc, 1.0, v107, 1.0
	v_mul_f32_e32 v115, v114, v112
	v_fma_f32 v116, -v111, v115, v114
	v_fmac_f32_e32 v115, v116, v112
	v_fma_f32 v111, -v111, v115, v114
	v_div_fmas_f32 v111, v111, v112, v115
	v_div_fixup_f32 v210, v111, v107, 1.0
	v_div_scale_f32 v107, s[10:11], v110, v110, 1.0
	v_rcp_f32_e32 v111, v107
	v_pk_mul_f32 v[108:109], v[108:109], v[210:211]
	v_pk_mul_f32 v[90:91], v[90:91], v[210:211]
	v_pk_fma_f32 v[108:109], v[22:23], v[108:109], v[18:19]
	v_fma_f32 v112, -v107, v111, 1.0
	v_fmac_f32_e32 v111, v112, v111
	v_div_scale_f32 v112, vcc, 1.0, v110, 1.0
	v_mul_f32_e32 v114, v112, v111
	v_fma_f32 v115, -v107, v114, v112
	v_fmac_f32_e32 v114, v115, v111
	v_fma_f32 v107, -v107, v114, v112
	v_div_fmas_f32 v107, v107, v111, v114
	v_div_fixup_f32 v213, v107, v110, 1.0
	v_div_scale_f32 v107, s[10:11], v113, v113, 1.0
	v_rcp_f32_e32 v110, v107
	v_pk_fma_f32 v[90:91], v[24:25], v[90:91], v[32:33]
	v_pk_mul_f32 v[86:87], v[86:87], v[210:211]
	v_pk_mul_f32 v[82:83], v[82:83], v[210:211]
	v_fma_f32 v111, -v107, v110, 1.0
	v_fmac_f32_e32 v110, v111, v110
	v_div_scale_f32 v111, vcc, 1.0, v113, 1.0
	v_mul_f32_e32 v112, v111, v110
	v_fma_f32 v114, -v107, v112, v111
	v_fmac_f32_e32 v112, v114, v110
	v_fma_f32 v107, -v107, v112, v111
	v_div_fmas_f32 v107, v107, v110, v112
	v_div_fixup_f32 v212, v107, v113, 1.0
	v_pk_mul_f32 v[110:111], v[190:191], v[212:213]
	v_pk_mul_f32 v[112:113], v[194:195], v[210:211]
	v_pk_fma_f32 v[110:111], v[44:45], v[110:111], v[42:43]
	v_pk_fma_f32 v[112:113], v[10:11], v[112:113], v[8:9]
	v_bfe_u32 v107, v111, 16, 1
	v_bfe_u32 v114, v110, 16, 1
	v_bfe_u32 v115, v113, 16, 1
	v_bfe_u32 v116, v112, 16, 1
	v_add3_u32 v199, v112, v116, s37
	v_add3_u32 v200, v113, v115, s37
	v_add3_u32 v201, v110, v114, s37
	v_add3_u32 v202, v111, v107, s37
	v_pk_mul_f32 v[110:111], v[196:197], v[212:213]
	v_pk_mul_f32 v[112:113], v[204:205], v[210:211]
	v_pk_fma_f32 v[110:111], v[48:49], v[110:111], v[46:47]
	v_pk_fma_f32 v[112:113], v[14:15], v[112:113], v[12:13]
	v_bfe_u32 v107, v111, 16, 1
	v_bfe_u32 v114, v110, 16, 1
	v_bfe_u32 v115, v113, 16, 1
	v_bfe_u32 v116, v112, 16, 1
	v_add3_u32 v190, v112, v116, s37
	v_add3_u32 v191, v113, v115, s37
	v_add3_u32 v192, v110, v114, s37
	v_add3_u32 v198, v111, v107, s37
	v_pk_mul_f32 v[110:111], v[206:207], v[212:213]
	v_pk_mul_f32 v[112:113], v[208:209], v[210:211]
	v_pk_fma_f32 v[110:111], v[52:53], v[110:111], v[50:51]
	v_pk_fma_f32 v[112:113], v[20:21], v[112:113], v[16:17]
	v_pk_mul_f32 v[92:93], v[92:93], v[212:213]
	v_bfe_u32 v107, v111, 16, 1
	v_bfe_u32 v114, v110, 16, 1
	v_bfe_u32 v116, v112, 16, 1
	v_pk_fma_f32 v[92:93], v[56:57], v[92:93], v[54:55]
	v_pk_mul_f32 v[88:89], v[88:89], v[212:213]
	v_add3_u32 v127, v112, v116, s37
; #define LAS __attribute__((address_space(3)))
; __device__ __forceinline__ unsigned f2bf(float f) { unsigned u = __builtin_bit_cast(unsigned, f); return (u + 0x7fffu + ((u >> 16) & 1u)) >> 16; }
; __device__ __forceinline__ void gmlp_unit(LAS unsigned char* lds, const bf16_t* U, const bf16_t* VG, const bf16_t* Wg, const float* lng, const float* lnb, const float* bias, bf16_t* Y, int blk, int wid0) {
;     ...
;         for (int u = 0; u < 8; ++u) { const bf16_t* vp = VG + (tok0 + wid * 16 + t8 + u) * 512 + lane;
; #pragma unroll
;             for (int i = 0; i < 8; ++i) v[u][i] = bf2f(vp[64 * i]); }
; #pragma unroll
;         for (int u = 0; u < 8; ++u) { const int s = wid * 16 + t8 + u; float sum = 0.f;
; #pragma unroll
;             for (int i = 0; i < 8; ++i) sum += v[u][i];
;             const float mean = wave_sum(sum, lane) * (1.0f / 512.0f); float q = 0.f;
; #pragma unroll
;             for (int i = 0; i < 8; ++i) { v[u][i] -= mean; q += v[u][i] * v[u][i]; }
;             const float rstd = 1.0f / sqrtf(wave_sum(q, lane) * (1.0f / 512.0f) + EPS);
; #pragma unroll
;             for (int i = 0; i < 8; ++i) { const int c = lane + 64 * i; const float y = v[u][i] * rstd * lg[i] + lb[i];
;                 *(LAS bf16_t*)(lds + c * 256 + ((((s >> 3) ^ (c & 15))) << 4) + (s & 7) * 2) = (bf16_t)f2bf(y); } }
	v_add3_u32 v188, v110, v114, s37
	v_add3_u32 v189, v111, v107, s37
	v_bfe_u32 v107, v93, 16, 1
	v_bfe_u32 v110, v92, 16, 1
	v_bfe_u32 v112, v108, 16, 1
	v_pk_fma_f32 v[88:89], v[60:61], v[88:89], v[58:59]
	v_pk_mul_f32 v[84:85], v[84:85], v[212:213]
	v_add3_u32 v123, v108, v112, s37
	v_add3_u32 v125, v92, v110, s37
	v_add3_u32 v126, v93, v107, s37
	v_bfe_u32 v92, v89, 16, 1
	v_bfe_u32 v93, v88, 16, 1
	v_bfe_u32 v107, v91, 16, 1
	v_bfe_u32 v108, v90, 16, 1
	v_pk_fma_f32 v[86:87], v[26:27], v[86:87], v[34:35]
	v_pk_fma_f32 v[84:85], v[64:65], v[84:85], v[62:63]
	v_pk_mul_f32 v[80:81], v[80:81], v[212:213]
	v_bfe_u32 v115, v113, 16, 1
	v_add3_u32 v119, v90, v108, s37
	v_add3_u32 v120, v91, v107, s37
	v_add3_u32 v121, v88, v93, s37
	v_add3_u32 v122, v89, v92, s37
	v_bfe_u32 v88, v85, 16, 1
	v_bfe_u32 v89, v84, 16, 1
	v_bfe_u32 v90, v87, 16, 1
	v_bfe_u32 v91, v86, 16, 1
	v_pk_fma_f32 v[82:83], v[28:29], v[82:83], v[36:37]
	v_pk_fma_f32 v[80:81], v[68:69], v[80:81], v[66:67]
	v_pk_mul_f32 v[76:77], v[76:77], v[212:213]
	v_pk_mul_f32 v[78:79], v[78:79], v[210:211]
	s_movk_i32 s10, 0x1000
	v_add3_u32 v187, v113, v115, s37
	v_bfe_u32 v111, v109, 16, 1
	v_add3_u32 v115, v86, v91, s37
	v_add3_u32 v116, v87, v90, s37
	v_add3_u32 v117, v84, v89, s37
	v_add3_u32 v118, v85, v88, s37
	v_bfe_u32 v84, v81, 16, 1
	v_bfe_u32 v85, v80, 16, 1
	v_bfe_u32 v86, v83, 16, 1
	v_bfe_u32 v87, v82, 16, 1
	v_pk_fma_f32 v[78:79], v[30:31], v[78:79], v[38:39]
	v_pk_fma_f32 v[76:77], v[72:73], v[76:77], v[70:71]
	v_add_co_u32_e32 v74, vcc, s10, v74
	v_add3_u32 v124, v109, v111, s37
	v_add3_u32 v111, v82, v87, s37
	v_add3_u32 v112, v83, v86, s37
	v_add3_u32 v113, v80, v85, s37
	v_add3_u32 v114, v81, v84, s37
	v_bfe_u32 v80, v77, 16, 1
	v_bfe_u32 v81, v76, 16, 1
	v_bfe_u32 v82, v79, 16, 1
	v_bfe_u32 v83, v78, 16, 1
	v_addc_co_u32_e32 v75, vcc, 0, v75, vcc
	v_add3_u32 v107, v78, v83, s37
	v_add3_u32 v108, v79, v82, s37
	v_add3_u32 v109, v76, v81, s37
	v_add3_u32 v110, v77, v80, s37
	flat_load_ushort v78, v[74:75]
	flat_load_ushort v79, v[74:75] offset:1024
	flat_load_ushort v76, v[74:75] offset:2048
	flat_load_ushort v77, v[74:75] offset:3072
	flat_load_ushort v82, v[74:75] offset:128
	flat_load_ushort v83, v[74:75] offset:1152
	flat_load_ushort v80, v[74:75] offset:2176
	flat_load_ushort v81, v[74:75] offset:3200
	flat_load_ushort v90, v[74:75] offset:256
	flat_load_ushort v91, v[74:75] offset:1280
	flat_load_ushort v88, v[74:75] offset:2304
	flat_load_ushort v89, v[74:75] offset:3328
	flat_load_ushort v194, v[74:75] offset:384
	flat_load_ushort v195, v[74:75] offset:1408
	flat_load_ushort v92, v[74:75] offset:2432
	flat_load_ushort v93, v[74:75] offset:3456
	flat_load_ushort v203, v[74:75] offset:512
	flat_load_ushort v204, v[74:75] offset:1536
	flat_load_ushort v196, v[74:75] offset:2560
	flat_load_ushort v197, v[74:75] offset:3584
	flat_load_ushort v240, v[74:75] offset:640
	flat_load_ushort v208, v[74:75] offset:1664
	flat_load_ushort v206, v[74:75] offset:2688
	flat_load_ushort v207, v[74:75] offset:3712
	flat_load_ushort v241, v[74:75] offset:768
	flat_load_ushort v212, v[74:75] offset:1792
	flat_load_ushort v210, v[74:75] offset:2816
	flat_load_ushort v211, v[74:75] offset:3840
	flat_load_ushort v242, v[74:75] offset:896
	flat_load_ushort v214, v[74:75] offset:1920
	flat_load_ushort v215, v[74:75] offset:2944
	flat_load_ushort v74, v[74:75] offset:3968
	v_perm_b32 v189, v189, v188, s33
	v_perm_b32 v188, v187, v127, s33
	s_waitcnt vmcnt(0) lgkmcnt(0)
	v_lshlrev_b32_e32 v78, 16, v78
	v_lshlrev_b32_e32 v79, 16, v79
	v_lshlrev_b32_e32 v83, 16, v83
	v_lshlrev_b32_e32 v82, 16, v82
	v_pk_add_f32 v[84:85], v[78:79], 0 op_sel_hi:[1,0]
	v_lshlrev_b32_e32 v205, 16, v204
	v_lshlrev_b32_e32 v204, 16, v203
	s_nop 0
	s_nop 0
	s_nop 0
	s_nop 0
	v_pk_add_f32 v[84:85], v[84:85], v[82:83]
	v_lshlrev_b32_e32 v91, 16, v91
	v_lshlrev_b32_e32 v90, 16, v90
	v_lshlrev_b32_e32 v77, 16, v77
	v_lshlrev_b32_e32 v76, 16, v76
	v_lshlrev_b32_e32 v195, 16, v195
	v_lshlrev_b32_e32 v194, 16, v194
	v_pk_add_f32 v[84:85], v[84:85], v[90:91]
	v_lshlrev_b32_e32 v81, 16, v81
	v_lshlrev_b32_e32 v80, 16, v80
	v_pk_add_f32 v[86:87], v[76:77], 0 op_sel_hi:[1,0]
	v_pk_add_f32 v[84:85], v[84:85], v[194:195]
	v_pk_add_f32 v[86:87], v[86:87], v[80:81]
	v_lshlrev_b32_e32 v89, 16, v89
	v_lshlrev_b32_e32 v88, 16, v88
	v_pk_add_f32 v[84:85], v[84:85], v[204:205]
	v_lshlrev_b32_e32 v93, 16, v93
	v_lshlrev_b32_e32 v92, 16, v92
	v_pk_add_f32 v[86:87], v[86:87], v[88:89]
	v_lshlrev_b32_e32 v197, 16, v197
	v_lshlrev_b32_e32 v196, 16, v196
	v_pk_add_f32 v[86:87], v[86:87], v[92:93]
	s_nop 0
	v_lshlrev_b32_e32 v209, 16, v208
	v_lshlrev_b32_e32 v208, 16, v240
	s_nop 0
	s_nop 0
	s_nop 0
	s_nop 0
	v_pk_add_f32 v[84:85], v[84:85], v[208:209]
	v_lshlrev_b32_e32 v207, 16, v207
	v_lshlrev_b32_e32 v206, 16, v206
	v_pk_add_f32 v[86:87], v[86:87], v[196:197]
	s_nop 0
	v_lshlrev_b32_e32 v213, 16, v212
	v_lshlrev_b32_e32 v212, 16, v241
	s_nop 0
	s_nop 0
	s_nop 0
	s_nop 0
	s_nop 0
	v_pk_add_f32 v[84:85], v[84:85], v[212:213]
	v_lshlrev_b32_e32 v211, 16, v211
	v_lshlrev_b32_e32 v210, 16, v210
	v_pk_add_f32 v[86:87], v[86:87], v[206:207]
	s_nop 0
	v_lshlrev_b32_e32 v75, 16, v74
	v_lshlrev_b32_e32 v74, 16, v215
	v_lshlrev_b32_e32 v215, 16, v214
	v_lshlrev_b32_e32 v214, 16, v242
	v_pk_add_f32 v[84:85], v[84:85], v[214:215]
	ds_bpermute_b32 v220, v96, v84
	ds_bpermute_b32 v221, v96, v85
	v_pk_add_f32 v[86:87], v[86:87], v[210:211]
	s_waitcnt lgkmcnt(0)
	v_pk_add_f32 v[84:85], v[84:85], v[220:221]
	v_pk_add_f32 v[86:87], v[86:87], v[74:75]
	ds_bpermute_b32 v222, v96, v86
	ds_bpermute_b32 v223, v96, v87
	ds_bpermute_b32 v220, v97, v84
	ds_bpermute_b32 v221, v97, v85
	s_waitcnt lgkmcnt(2)
; __device__ __forceinline__ void gmlp_unit(LAS unsigned char* lds, const bf16_t* U, const bf16_t* VG, const bf16_t* Wg, const float* lng, const float* lnb, const float* bias, bf16_t* Y, int blk, int wid0) {
;     ...
;         for (int u = 0; u < 8; ++u) { const int s = wid * 16 + t8 + u; float sum = 0.f;
; #pragma unroll
;             for (int i = 0; i < 8; ++i) sum += v[u][i];
;             const float mean = wave_sum(sum, lane) * (1.0f / 512.0f); float q = 0.f;
; #pragma unroll
;             for (int i = 0; i < 8; ++i) { v[u][i] -= mean; q += v[u][i] * v[u][i]; }
;             const float rstd = 1.0f / sqrtf(wave_sum(q, lane) * (1.0f / 512.0f) + EPS);
	v_pk_add_f32 v[86:87], v[86:87], v[222:223]
	ds_bpermute_b32 v222, v97, v86
	ds_bpermute_b32 v223, v97, v87
	s_waitcnt lgkmcnt(2)
	v_pk_add_f32 v[84:85], v[84:85], v[220:221]
	ds_bpermute_b32 v220, v98, v84
	ds_bpermute_b32 v221, v98, v85
	s_waitcnt lgkmcnt(2)
	v_pk_add_f32 v[86:87], v[86:87], v[222:223]
	ds_bpermute_b32 v222, v98, v86
	ds_bpermute_b32 v223, v98, v87
	s_waitcnt lgkmcnt(2)
	v_pk_add_f32 v[84:85], v[84:85], v[220:221]
	ds_bpermute_b32 v220, v99, v84
	ds_bpermute_b32 v221, v99, v85
	s_waitcnt lgkmcnt(2)
	v_pk_add_f32 v[86:87], v[86:87], v[222:223]
	ds_bpermute_b32 v222, v99, v86
	ds_bpermute_b32 v223, v99, v87
	s_waitcnt lgkmcnt(2)
	v_pk_add_f32 v[84:85], v[84:85], v[220:221]
	ds_bpermute_b32 v220, v100, v84
	ds_bpermute_b32 v221, v100, v85
	s_waitcnt lgkmcnt(2)
	v_pk_add_f32 v[86:87], v[86:87], v[222:223]
	ds_bpermute_b32 v222, v100, v86
	ds_bpermute_b32 v223, v100, v87
	s_waitcnt lgkmcnt(2)
	v_pk_add_f32 v[84:85], v[84:85], v[220:221]
	ds_bpermute_b32 v220, v101, v84
	ds_bpermute_b32 v221, v101, v85
	s_waitcnt lgkmcnt(2)
	v_pk_add_f32 v[86:87], v[86:87], v[222:223]
	ds_bpermute_b32 v222, v101, v86
	ds_bpermute_b32 v223, v101, v87
	s_waitcnt lgkmcnt(2)
	v_pk_add_f32 v[220:221], v[84:85], v[220:221]
	s_waitcnt lgkmcnt(0)
	v_pk_add_f32 v[222:223], v[86:87], v[222:223]
	v_pk_fma_f32 v[230:231], v[220:221], s[16:17], v[82:83] op_sel_hi:[1,0,1] neg_lo:[1,0,0] neg_hi:[1,0,0]
	v_pk_fma_f32 v[226:227], v[220:221], s[16:17], v[78:79] op_sel_hi:[1,0,1] neg_lo:[1,0,0] neg_hi:[1,0,0]
	v_mul_f32_e32 v203, v230, v230
	v_fmac_f32_e32 v203, v226, v226
	v_pk_fma_f32 v[234:235], v[220:221], s[16:17], v[90:91] op_sel_hi:[1,0,1] neg_lo:[1,0,0] neg_hi:[1,0,0]
	v_pk_fma_f32 v[90:91], v[222:223], s[16:17], v[92:93] op_sel_hi:[1,0,1] neg_lo:[1,0,0] neg_hi:[1,0,0]
	v_fmac_f32_e32 v203, v234, v234
	v_pk_fma_f32 v[92:93], v[220:221], s[16:17], v[194:195] op_sel_hi:[1,0,1] neg_lo:[1,0,0] neg_hi:[1,0,0]
	v_pk_fma_f32 v[224:225], v[222:223], s[16:17], v[76:77] op_sel_hi:[1,0,1] neg_lo:[1,0,0] neg_hi:[1,0,0]
	v_pk_fma_f32 v[228:229], v[222:223], s[16:17], v[80:81] op_sel_hi:[1,0,1] neg_lo:[1,0,0] neg_hi:[1,0,0]
	v_pk_fma_f32 v[232:233], v[222:223], s[16:17], v[88:89] op_sel_hi:[1,0,1] neg_lo:[1,0,0] neg_hi:[1,0,0]
	v_fmac_f32_e32 v203, v92, v92
	v_pk_fma_f32 v[88:89], v[220:221], s[16:17], v[204:205] op_sel_hi:[1,0,1] neg_lo:[1,0,0] neg_hi:[1,0,0]
	v_pk_fma_f32 v[80:81], v[220:221], s[16:17], v[212:213] op_sel_hi:[1,0,1] neg_lo:[1,0,0] neg_hi:[1,0,0]
	v_pk_fma_f32 v[76:77], v[220:221], s[16:17], v[214:215] op_sel_hi:[1,0,1] neg_lo:[1,0,0] neg_hi:[1,0,0]
	v_fmac_f32_e32 v203, v88, v88
	v_pk_fma_f32 v[84:85], v[220:221], s[16:17], v[208:209] op_sel_hi:[1,0,1] neg_lo:[1,0,0] neg_hi:[1,0,0]
	v_mov_b32_e32 v194, v76
	v_mov_b32_e32 v195, v80
	v_fmac_f32_e32 v203, v84, v84
	v_pk_mul_f32 v[194:195], v[194:195], v[194:195]
	v_pk_fma_f32 v[86:87], v[222:223], s[16:17], v[196:197] op_sel_hi:[1,0,1] neg_lo:[1,0,0] neg_hi:[1,0,0]
	v_add_f32_e32 v195, v195, v203
	v_add_f32_e32 v194, v194, v195
	ds_bpermute_b32 v195, v96, v194
	v_pk_fma_f32 v[78:79], v[222:223], s[16:17], v[210:211] op_sel_hi:[1,0,1] neg_lo:[1,0,0] neg_hi:[1,0,0]
	v_pk_fma_f32 v[74:75], v[222:223], s[16:17], v[74:75] op_sel_hi:[1,0,1] neg_lo:[1,0,0] neg_hi:[1,0,0]
	v_pk_fma_f32 v[82:83], v[222:223], s[16:17], v[206:207] op_sel_hi:[1,0,1] neg_lo:[1,0,0] neg_hi:[1,0,0]
	s_waitcnt lgkmcnt(0)
	v_add_f32_e32 v194, v194, v195
	ds_bpermute_b32 v195, v97, v194
	s_waitcnt lgkmcnt(0)
	v_add_f32_e32 v194, v194, v195
	ds_bpermute_b32 v195, v98, v194
	s_waitcnt lgkmcnt(0)
	v_add_f32_e32 v194, v194, v195
	ds_bpermute_b32 v195, v99, v194
	s_waitcnt lgkmcnt(0)
	v_add_f32_e32 v194, v194, v195
	ds_bpermute_b32 v195, v100, v194
	s_waitcnt lgkmcnt(0)
	v_add_f32_e32 v194, v194, v195
	ds_bpermute_b32 v195, v101, v194
	s_waitcnt lgkmcnt(0)
	v_add_f32_e32 v194, v194, v195
	v_fmamk_f32 v194, v194, 0x3b000000, v217
	v_cmp_gt_f32_e32 vcc, s59, v194
	v_mul_f32_e32 v195, 0x4f800000, v194
	s_nop 0
	v_cndmask_b32_e32 v194, v194, v195, vcc
	v_sqrt_f32_e32 v195, v194
	s_nop 0
	v_add_u32_e32 v196, -1, v195
	v_fma_f32 v197, -v196, v195, v194
	v_cmp_ge_f32_e64 s[40:41], 0, v197
	v_add_u32_e32 v197, 1, v195
	s_nop 0
	v_cndmask_b32_e64 v196, v195, v196, s[40:41]
	v_fma_f32 v195, -v197, v195, v194
	v_cmp_lt_f32_e64 s[40:41], 0, v195
	s_nop 1
	v_cndmask_b32_e64 v195, v196, v197, s[40:41]
	v_mul_f32_e32 v197, v231, v231
	v_fmac_f32_e32 v197, v227, v227
	v_mul_f32_e32 v196, 0x37800000, v195
	v_fmac_f32_e32 v197, v235, v235
	v_cndmask_b32_e32 v195, v195, v196, vcc
	v_cmp_class_f32_e32 vcc, v194, v218
	v_fmac_f32_e32 v197, v93, v93
	v_fmac_f32_e32 v197, v89, v89
	v_cndmask_b32_e32 v196, v195, v194, vcc
	v_mov_b32_e32 v194, v77
	v_mov_b32_e32 v195, v81
	v_fmac_f32_e32 v197, v85, v85
	v_pk_mul_f32 v[194:195], v[194:195], v[194:195]
	s_nop 0
	v_add_f32_e32 v195, v195, v197
	v_add_f32_e32 v194, v194, v195
	ds_bpermute_b32 v195, v96, v194
	s_waitcnt lgkmcnt(0)
	v_add_f32_e32 v194, v194, v195
	ds_bpermute_b32 v195, v97, v194
	s_waitcnt lgkmcnt(0)
	v_add_f32_e32 v194, v194, v195
	ds_bpermute_b32 v195, v98, v194
	s_waitcnt lgkmcnt(0)
	v_add_f32_e32 v194, v194, v195
	ds_bpermute_b32 v195, v99, v194
	s_waitcnt lgkmcnt(0)
	v_add_f32_e32 v194, v194, v195
	ds_bpermute_b32 v195, v100, v194
	s_waitcnt lgkmcnt(0)
	v_add_f32_e32 v194, v194, v195
	ds_bpermute_b32 v195, v101, v194
	s_waitcnt lgkmcnt(0)
; __device__ __forceinline__ void gmlp_unit(LAS unsigned char* lds, const bf16_t* U, const bf16_t* VG, const bf16_t* Wg, const float* lng, const float* lnb, const float* bias, bf16_t* Y, int blk, int wid0) {
;     ...
;             for (int i = 0; i < 8; ++i) { v[u][i] -= mean; q += v[u][i] * v[u][i]; }
;             const float rstd = 1.0f / sqrtf(wave_sum(q, lane) * (1.0f / 512.0f) + EPS);
; #pragma unroll
;             for (int i = 0; i < 8; ++i) { const int c = lane + 64 * i; const float y = v[u][i] * rstd * lg[i] + lb[i];
	v_add_f32_e32 v194, v194, v195
	v_fmamk_f32 v194, v194, 0x3b000000, v217
	v_cmp_gt_f32_e32 vcc, s59, v194
	v_mul_f32_e32 v195, 0x4f800000, v194
	s_nop 0
	v_cndmask_b32_e32 v194, v194, v195, vcc
	v_sqrt_f32_e32 v195, v194
	s_nop 0
	v_add_u32_e32 v197, -1, v195
	v_fma_f32 v203, -v197, v195, v194
	v_cmp_ge_f32_e64 s[40:41], 0, v203
	v_add_u32_e32 v203, 1, v195
	s_nop 0
	v_cndmask_b32_e64 v197, v195, v197, s[40:41]
	v_fma_f32 v195, -v203, v195, v194
	v_cmp_lt_f32_e64 s[40:41], 0, v195
	s_nop 1
	v_cndmask_b32_e64 v195, v197, v203, s[40:41]
	v_mul_f32_e32 v203, v228, v228
	v_fmac_f32_e32 v203, v224, v224
	v_mul_f32_e32 v197, 0x37800000, v195
	v_fmac_f32_e32 v203, v232, v232
	v_cndmask_b32_e32 v195, v195, v197, vcc
	v_cmp_class_f32_e32 vcc, v194, v218
	v_fmac_f32_e32 v203, v90, v90
	v_fmac_f32_e32 v203, v86, v86
	v_cndmask_b32_e32 v197, v195, v194, vcc
	v_mov_b32_e32 v194, v74
	v_mov_b32_e32 v195, v78
	v_fmac_f32_e32 v203, v82, v82
	v_pk_mul_f32 v[194:195], v[194:195], v[194:195]
	s_nop 0
	v_add_f32_e32 v195, v195, v203
	v_add_f32_e32 v194, v194, v195
	ds_bpermute_b32 v195, v96, v194
	s_waitcnt lgkmcnt(0)
	v_add_f32_e32 v194, v194, v195
	ds_bpermute_b32 v195, v97, v194
	s_waitcnt lgkmcnt(0)
	v_add_f32_e32 v194, v194, v195
	ds_bpermute_b32 v195, v98, v194
	s_waitcnt lgkmcnt(0)
	v_add_f32_e32 v194, v194, v195
	ds_bpermute_b32 v195, v99, v194
	s_waitcnt lgkmcnt(0)
	v_add_f32_e32 v194, v194, v195
	ds_bpermute_b32 v195, v100, v194
	s_waitcnt lgkmcnt(0)
	v_add_f32_e32 v194, v194, v195
	ds_bpermute_b32 v195, v101, v194
	s_waitcnt lgkmcnt(0)
	v_add_f32_e32 v194, v194, v195
	v_fmamk_f32 v194, v194, 0x3b000000, v217
	v_cmp_gt_f32_e32 vcc, s59, v194
	v_mul_f32_e32 v195, 0x4f800000, v194
	s_nop 0
	v_cndmask_b32_e32 v194, v194, v195, vcc
	v_sqrt_f32_e32 v195, v194
	s_nop 0
	v_add_u32_e32 v203, -1, v195
	v_fma_f32 v204, -v203, v195, v194
	v_cmp_ge_f32_e64 s[40:41], 0, v204
	v_add_u32_e32 v204, 1, v195
	s_nop 0
	v_cndmask_b32_e64 v203, v195, v203, s[40:41]
	v_fma_f32 v195, -v204, v195, v194
	v_cmp_lt_f32_e64 s[40:41], 0, v195
	s_nop 1
	v_cndmask_b32_e64 v195, v203, v204, s[40:41]
	v_mul_f32_e32 v204, v229, v229
	v_fmac_f32_e32 v204, v225, v225
	v_mul_f32_e32 v203, 0x37800000, v195
	v_fmac_f32_e32 v204, v233, v233
	v_cndmask_b32_e32 v195, v195, v203, vcc
	v_cmp_class_f32_e32 vcc, v194, v218
	v_fmac_f32_e32 v204, v91, v91
	v_fmac_f32_e32 v204, v87, v87
	v_cndmask_b32_e32 v203, v195, v194, vcc
	v_mov_b32_e32 v194, v75
	v_mov_b32_e32 v195, v79
	v_fmac_f32_e32 v204, v83, v83
	v_pk_mul_f32 v[194:195], v[194:195], v[194:195]
	s_nop 0
	v_add_f32_e32 v195, v195, v204
	v_add_f32_e32 v194, v194, v195
	ds_bpermute_b32 v195, v96, v194
	s_waitcnt lgkmcnt(0)
	v_add_f32_e32 v194, v194, v195
	ds_bpermute_b32 v195, v97, v194
	s_waitcnt lgkmcnt(0)
	v_add_f32_e32 v194, v194, v195
	ds_bpermute_b32 v195, v98, v194
	s_waitcnt lgkmcnt(0)
	v_add_f32_e32 v194, v194, v195
	ds_bpermute_b32 v195, v99, v194
	s_waitcnt lgkmcnt(0)
	v_add_f32_e32 v194, v194, v195
	ds_bpermute_b32 v195, v100, v194
	s_waitcnt lgkmcnt(0)
	v_add_f32_e32 v194, v194, v195
	ds_bpermute_b32 v195, v101, v194
	s_waitcnt lgkmcnt(0)
	v_add_f32_e32 v194, v194, v195
	v_fmamk_f32 v194, v194, 0x3b000000, v217
	v_cmp_gt_f32_e32 vcc, s59, v194
	v_mul_f32_e32 v195, 0x4f800000, v194
	s_nop 0
	v_cndmask_b32_e32 v194, v194, v195, vcc
	v_sqrt_f32_e32 v195, v194
	s_nop 0
	v_add_u32_e32 v204, -1, v195
	v_fma_f32 v205, -v204, v195, v194
	v_cmp_ge_f32_e64 s[40:41], 0, v205
	v_add_u32_e32 v205, 1, v195
	s_nop 0
	v_cndmask_b32_e64 v204, v195, v204, s[40:41]
	v_fma_f32 v195, -v205, v195, v194
	v_cmp_lt_f32_e64 s[40:41], 0, v195
	s_nop 1
	v_cndmask_b32_e64 v195, v204, v205, s[40:41]
	v_mul_f32_e32 v204, 0x37800000, v195
	v_cndmask_b32_e32 v195, v195, v204, vcc
	v_cmp_class_f32_e32 vcc, v194, v218
	s_mov_b64 s[40:41], 0
	s_nop 0
	v_cndmask_b32_e32 v194, v195, v194, vcc
	v_div_scale_f32 v195, s[10:11], v197, v197, 1.0
	v_rcp_f32_e32 v204, v195
	s_nop 0
	v_fma_f32 v205, -v195, v204, 1.0
	v_fmac_f32_e32 v204, v205, v204
	v_div_scale_f32 v205, vcc, 1.0, v197, 1.0
	v_mul_f32_e32 v206, v205, v204
	v_fma_f32 v207, -v195, v206, v205
	v_fmac_f32_e32 v206, v207, v204
	v_fma_f32 v195, -v195, v206, v205
	v_div_fmas_f32 v195, v195, v204, v206
	v_div_fixup_f32 v205, v195, v197, 1.0
	v_div_scale_f32 v195, s[10:11], v196, v196, 1.0
	v_rcp_f32_e32 v197, v195
	s_nop 0
	v_fma_f32 v204, -v195, v197, 1.0
	v_fmac_f32_e32 v197, v204, v197
	v_div_scale_f32 v204, vcc, 1.0, v196, 1.0
	v_mul_f32_e32 v206, v204, v197
	v_fma_f32 v207, -v195, v206, v204
	v_fmac_f32_e32 v206, v207, v197
	v_fma_f32 v195, -v195, v206, v204
	v_div_fmas_f32 v195, v195, v197, v206
	v_div_fixup_f32 v204, v195, v196, 1.0
	v_div_scale_f32 v195, s[10:11], v194, v194, 1.0
	v_rcp_f32_e32 v196, v195
	v_pk_mul_f32 v[92:93], v[92:93], v[204:205]
	v_pk_mul_f32 v[88:89], v[88:89], v[204:205]
	v_pk_fma_f32 v[92:93], v[22:23], v[92:93], v[18:19]
	v_fma_f32 v197, -v195, v196, 1.0
	v_fmac_f32_e32 v196, v197, v196
	v_div_scale_f32 v197, vcc, 1.0, v194, 1.0
	v_mul_f32_e32 v206, v197, v196
	v_fma_f32 v207, -v195, v206, v197
	v_fmac_f32_e32 v206, v207, v196
	v_fma_f32 v195, -v195, v206, v197
	v_div_fmas_f32 v195, v195, v196, v206
	v_div_fixup_f32 v207, v195, v194, 1.0
	v_div_scale_f32 v194, s[10:11], v203, v203, 1.0
	v_rcp_f32_e32 v195, v194
	v_pk_fma_f32 v[88:89], v[24:25], v[88:89], v[32:33]
	v_pk_mul_f32 v[84:85], v[84:85], v[204:205]
	v_pk_mul_f32 v[80:81], v[80:81], v[204:205]
	v_fma_f32 v196, -v194, v195, 1.0
	v_fmac_f32_e32 v195, v196, v195
	v_div_scale_f32 v196, vcc, 1.0, v203, 1.0
	v_mul_f32_e32 v197, v196, v195
	v_fma_f32 v206, -v194, v197, v196
	v_fmac_f32_e32 v197, v206, v195
	v_fma_f32 v194, -v194, v197, v196
; #define LAS __attribute__((address_space(3)))
; __device__ __forceinline__ unsigned f2bf(float f) { unsigned u = __builtin_bit_cast(unsigned, f); return (u + 0x7fffu + ((u >> 16) & 1u)) >> 16; }
; __device__ __forceinline__ void gmlp_unit(LAS unsigned char* lds, const bf16_t* U, const bf16_t* VG, const bf16_t* Wg, const float* lng, const float* lnb, const float* bias, bf16_t* Y, int blk, int wid0) {
;     ...
; #pragma unroll
;             for (int i = 0; i < 8; ++i) { const int c = lane + 64 * i; const float y = v[u][i] * rstd * lg[i] + lb[i];
;                 *(LAS bf16_t*)(lds + c * 256 + ((((s >> 3) ^ (c & 15))) << 4) + (s & 7) * 2) = (bf16_t)f2bf(y); } }
	v_div_fmas_f32 v194, v194, v195, v197
	v_div_fixup_f32 v206, v194, v203, 1.0
	v_pk_mul_f32 v[194:195], v[224:225], v[206:207]
	v_pk_mul_f32 v[196:197], v[226:227], v[204:205]
	v_pk_fma_f32 v[194:195], v[44:45], v[194:195], v[42:43]
	v_pk_fma_f32 v[196:197], v[10:11], v[196:197], v[8:9]
	v_bfe_u32 v203, v195, 16, 1
	v_bfe_u32 v208, v194, 16, 1
	v_bfe_u32 v209, v197, 16, 1
	v_bfe_u32 v210, v196, 16, 1
	v_add3_u32 v196, v196, v210, s37
	v_add3_u32 v209, v197, v209, s37
	v_add3_u32 v194, v194, v208, s37
	v_add3_u32 v195, v195, v203, s37
	v_perm_b32 v197, v195, v194, s33
	v_perm_b32 v196, v209, v196, s33
	v_perm_b32 v195, v202, v201, s33
	v_perm_b32 v194, v200, v199, s33
	ds_write_b128 v106, v[194:197]
	v_pk_mul_f32 v[194:195], v[228:229], v[206:207]
	v_pk_mul_f32 v[196:197], v[230:231], v[204:205]
	v_pk_fma_f32 v[194:195], v[48:49], v[194:195], v[46:47]
	v_pk_fma_f32 v[196:197], v[14:15], v[196:197], v[12:13]
	v_bfe_u32 v199, v195, 16, 1
	v_bfe_u32 v200, v194, 16, 1
	v_bfe_u32 v201, v197, 16, 1
	v_bfe_u32 v202, v196, 16, 1
	v_add3_u32 v196, v196, v202, s37
	v_add3_u32 v201, v197, v201, s37
	v_add3_u32 v194, v194, v200, s37
	v_add3_u32 v195, v195, v199, s37
	v_perm_b32 v197, v195, v194, s33
	v_perm_b32 v196, v201, v196, s33
	v_perm_b32 v195, v198, v192, s33
	v_perm_b32 v194, v191, v190, s33
	ds_write_b128 v106, v[194:197] offset:16384
	v_pk_mul_f32 v[190:191], v[232:233], v[206:207]
	v_pk_mul_f32 v[194:195], v[234:235], v[204:205]
	v_pk_fma_f32 v[190:191], v[52:53], v[190:191], v[50:51]
	v_pk_fma_f32 v[194:195], v[20:21], v[194:195], v[16:17]
	v_bfe_u32 v192, v191, 16, 1
	v_bfe_u32 v196, v190, 16, 1
	v_bfe_u32 v197, v195, 16, 1
	v_bfe_u32 v198, v194, 16, 1
	v_add3_u32 v194, v194, v198, s37
	v_add3_u32 v195, v195, v197, s37
	v_add3_u32 v190, v190, v196, s37
	v_add3_u32 v191, v191, v192, s37
	v_pk_mul_f32 v[90:91], v[90:91], v[206:207]
	v_perm_b32 v191, v191, v190, s33
	v_perm_b32 v190, v195, v194, s33
	v_pk_fma_f32 v[90:91], v[56:57], v[90:91], v[54:55]
	ds_write_b128 v106, v[188:191] offset:32768
	v_bfe_u32 v127, v91, 16, 1
	v_bfe_u32 v187, v90, 16, 1
	v_bfe_u32 v188, v93, 16, 1
	v_bfe_u32 v189, v92, 16, 1
	v_add3_u32 v92, v92, v189, s37
	v_add3_u32 v188, v93, v188, s37
	v_add3_u32 v90, v90, v187, s37
	v_add3_u32 v91, v91, v127, s37
	v_pk_mul_f32 v[86:87], v[86:87], v[206:207]
	v_perm_b32 v93, v91, v90, s33
	v_perm_b32 v92, v188, v92, s33
	v_perm_b32 v91, v126, v125, s33
	v_perm_b32 v90, v124, v123, s33
	v_pk_fma_f32 v[86:87], v[60:61], v[86:87], v[58:59]
	ds_write_b128 v106, v[90:93] offset:49152
	v_bfe_u32 v90, v87, 16, 1
	v_bfe_u32 v91, v86, 16, 1
	v_bfe_u32 v92, v89, 16, 1
	v_bfe_u32 v93, v88, 16, 1
	v_add3_u32 v88, v88, v93, s37
	v_add3_u32 v92, v89, v92, s37
	v_add3_u32 v86, v86, v91, s37
	v_add3_u32 v87, v87, v90, s37
	v_pk_mul_f32 v[82:83], v[82:83], v[206:207]
	v_perm_b32 v89, v87, v86, s33
	v_perm_b32 v88, v92, v88, s33
	v_perm_b32 v87, v122, v121, s33
	v_perm_b32 v86, v120, v119, s33
	v_pk_fma_f32 v[84:85], v[26:27], v[84:85], v[34:35]
	v_pk_fma_f32 v[82:83], v[64:65], v[82:83], v[62:63]
	ds_write_b128 v105, v[86:89]
	v_bfe_u32 v86, v83, 16, 1
	v_bfe_u32 v87, v82, 16, 1
	v_bfe_u32 v88, v85, 16, 1
	v_bfe_u32 v89, v84, 16, 1
	v_add3_u32 v84, v84, v89, s37
	v_add3_u32 v88, v85, v88, s37
	v_add3_u32 v82, v82, v87, s37
	v_add3_u32 v83, v83, v86, s37
	v_pk_mul_f32 v[78:79], v[78:79], v[206:207]
	v_perm_b32 v85, v83, v82, s33
	v_perm_b32 v84, v88, v84, s33
	v_perm_b32 v83, v118, v117, s33
	v_perm_b32 v82, v116, v115, s33
	v_pk_fma_f32 v[80:81], v[28:29], v[80:81], v[36:37]
	v_pk_fma_f32 v[78:79], v[68:69], v[78:79], v[66:67]
	ds_write_b128 v104, v[82:85]
	v_bfe_u32 v82, v79, 16, 1
	v_bfe_u32 v83, v78, 16, 1
	v_bfe_u32 v84, v81, 16, 1
	v_bfe_u32 v85, v80, 16, 1
	v_add3_u32 v80, v80, v85, s37
	v_add3_u32 v84, v81, v84, s37
	v_add3_u32 v78, v78, v83, s37
	v_add3_u32 v79, v79, v82, s37
	v_pk_mul_f32 v[74:75], v[74:75], v[206:207]
	v_pk_mul_f32 v[76:77], v[76:77], v[204:205]
	v_perm_b32 v81, v79, v78, s33
	v_perm_b32 v80, v84, v80, s33
	v_perm_b32 v79, v114, v113, s33
	v_perm_b32 v78, v112, v111, s33
	v_pk_fma_f32 v[76:77], v[30:31], v[76:77], v[38:39]
	v_pk_fma_f32 v[74:75], v[72:73], v[74:75], v[70:71]
	ds_write_b128 v103, v[78:81]
	v_bfe_u32 v78, v75, 16, 1
	v_bfe_u32 v79, v74, 16, 1
	v_bfe_u32 v80, v77, 16, 1
	v_bfe_u32 v81, v76, 16, 1
	v_add3_u32 v76, v76, v81, s37
	v_add3_u32 v80, v77, v80, s37
	v_add3_u32 v74, v74, v79, s37
	v_add3_u32 v75, v75, v78, s37
	v_perm_b32 v77, v75, v74, s33
	v_perm_b32 v76, v80, v76, s33
	v_perm_b32 v75, v110, v109, s33
	v_perm_b32 v74, v108, v107, s33
	s_and_b64 vcc, exec, s[38:39]
	ds_write_b128 v102, v[74:77]
	s_cbranch_vccz .LBB0_292
; #define LAS __attribute__((address_space(3)))
; __device__ __forceinline__ void gmlp_unit(LAS unsigned char* lds, const bf16_t* U, const bf16_t* VG, const bf16_t* Wg, const float* lng, const float* lnb, const float* bias, bf16_t* Y, int blk, int wid0) {
;     ...
;     __syncthreads();
;     f32x16 acc[2][4];
; #pragma unroll
;     for (int a = 0; a < 2; ++a)
; #pragma unroll
;         for (int b = 0; b < 4; ++b)
; #pragma unroll
;             for (int r = 0; r < 16; ++r) acc[a][b][r] = 0.f;
; #pragma unroll
;     for (int kk = 0; kk < 8; ++kk) {
;         if (kk < 4 || th) {
; #pragma unroll
;             for (int ci = 0; ci < 4; ++ci) { const int c = g * 128 + 32 * ci + i32;
;                 const bf16x8 vfr = *(const LAS bf16x8*)(lds + c * 256 + ((((2 * kk + hi) ^ (c & 15))) << 4));
;                 acc[0][ci] = __builtin_amdgcn_mfma_f32_32x32x16_bf16(vfr, wf[0][kk], acc[0][ci], 0, 0, 0);
;                 acc[1][ci] = __builtin_amdgcn_mfma_f32_32x32x16_bf16(vfr, wf[1][kk], acc[1][ci], 0, 0, 0); } }
;     }
	v_xor_b32_e32 v8, v184, v186
	v_lshlrev_b32_e32 v8, 4, v8
	v_lshlrev_b32_e32 v187, 8, v94
	v_add3_u32 v12, 0, v8, v187
	s_waitcnt lgkmcnt(0)
	s_barrier
	ds_read_b128 v[8:11], v12
	v_bitop3_b32 v188, v184, v186, 2 bitop3:0x36
	v_lshlrev_b32_e32 v188, 4, v188
	v_add3_u32 v192, 0, v188, v187
	ds_read_b128 v[188:191], v192
	s_waitcnt lgkmcnt(1)
	v_mfma_f32_32x32x16_bf16 v[112:127], v[8:11], v[0:3], 0
	s_cmp_lg_u32 s5, 0
	s_cselect_b64 s[40:41], -1, 0
	s_and_b64 vcc, exec, s[40:41]
	v_mfma_f32_32x32x16_bf16 v[48:63], v[8:11], v[4:7], 0
	ds_read_b128 v[8:11], v12 offset:8192
	s_waitcnt lgkmcnt(1)
	v_mfma_f32_32x32x16_bf16 v[112:127], v[188:191], v[176:179], v[112:127]
	v_mfma_f32_32x32x16_bf16 v[48:63], v[188:191], v[180:183], v[48:63]
	ds_read_b128 v[188:191], v192 offset:8192
	s_waitcnt lgkmcnt(1)
	v_mfma_f32_32x32x16_bf16 v[96:111], v[8:11], v[0:3], 0
	v_mfma_f32_32x32x16_bf16 v[32:47], v[8:11], v[4:7], 0
	ds_read_b128 v[8:11], v12 offset:16384
	s_waitcnt lgkmcnt(1)
	v_mfma_f32_32x32x16_bf16 v[96:111], v[188:191], v[176:179], v[96:111]
	v_mfma_f32_32x32x16_bf16 v[32:47], v[188:191], v[180:183], v[32:47]
	ds_read_b128 v[188:191], v192 offset:16384
	s_waitcnt lgkmcnt(1)
	v_mfma_f32_32x32x16_bf16 v[80:95], v[8:11], v[0:3], 0
	v_mfma_f32_32x32x16_bf16 v[16:31], v[8:11], v[4:7], 0
	ds_read_b128 v[8:11], v12 offset:24576
	s_waitcnt lgkmcnt(1)
	v_mfma_f32_32x32x16_bf16 v[80:95], v[188:191], v[176:179], v[80:95]
	v_mfma_f32_32x32x16_bf16 v[16:31], v[188:191], v[180:183], v[16:31]
	ds_read_b128 v[188:191], v192 offset:24576
	s_waitcnt lgkmcnt(1)
	v_mfma_f32_32x32x16_bf16 v[64:79], v[8:11], v[0:3], 0
	v_mfma_f32_32x32x16_bf16 v[0:15], v[8:11], v[4:7], 0
	s_waitcnt lgkmcnt(0)
	v_mfma_f32_32x32x16_bf16 v[64:79], v[188:191], v[176:179], v[64:79]
	v_bitop3_b32 v176, v184, v186, 4 bitop3:0x36
	v_lshlrev_b32_e32 v176, 4, v176
	v_mfma_f32_32x32x16_bf16 v[0:15], v[188:191], v[180:183], v[0:15]
	v_add3_u32 v180, 0, v176, v187
	ds_read_b128 v[176:179], v180
	s_waitcnt lgkmcnt(0)
	v_mfma_f32_32x32x16_bf16 v[112:127], v[176:179], v[168:171], v[112:127]
	v_mfma_f32_32x32x16_bf16 v[48:63], v[176:179], v[172:175], v[48:63]
	ds_read_b128 v[176:179], v180 offset:8192
	s_waitcnt lgkmcnt(0)
	v_mfma_f32_32x32x16_bf16 v[96:111], v[176:179], v[168:171], v[96:111]
	v_mfma_f32_32x32x16_bf16 v[32:47], v[176:179], v[172:175], v[32:47]
	ds_read_b128 v[176:179], v180 offset:16384
	s_waitcnt lgkmcnt(0)
	v_mfma_f32_32x32x16_bf16 v[80:95], v[176:179], v[168:171], v[80:95]
	v_mfma_f32_32x32x16_bf16 v[16:31], v[176:179], v[172:175], v[16:31]
	ds_read_b128 v[176:179], v180 offset:24576
	s_waitcnt lgkmcnt(0)
	v_mfma_f32_32x32x16_bf16 v[64:79], v[176:179], v[168:171], v[64:79]
	v_bitop3_b32 v168, v184, v186, 6 bitop3:0x36
	v_lshlrev_b32_e32 v168, 4, v168
	v_mfma_f32_32x32x16_bf16 v[0:15], v[176:179], v[172:175], v[0:15]
	v_add3_u32 v172, 0, v168, v187
	ds_read_b128 v[168:171], v172
	s_waitcnt lgkmcnt(0)
	v_mfma_f32_32x32x16_bf16 v[112:127], v[168:171], v[160:163], v[112:127]
	v_mfma_f32_32x32x16_bf16 v[48:63], v[168:171], v[164:167], v[48:63]
	ds_read_b128 v[168:171], v172 offset:8192
	s_waitcnt lgkmcnt(0)
	v_mfma_f32_32x32x16_bf16 v[96:111], v[168:171], v[160:163], v[96:111]
	v_mfma_f32_32x32x16_bf16 v[32:47], v[168:171], v[164:167], v[32:47]
	ds_read_b128 v[168:171], v172 offset:16384
	s_waitcnt lgkmcnt(0)
	v_mfma_f32_32x32x16_bf16 v[80:95], v[168:171], v[160:163], v[80:95]
	v_mfma_f32_32x32x16_bf16 v[16:31], v[168:171], v[164:167], v[16:31]
	ds_read_b128 v[168:171], v172 offset:24576
	s_waitcnt lgkmcnt(0)
	v_mfma_f32_32x32x16_bf16 v[64:79], v[168:171], v[160:163], v[64:79]
	v_mfma_f32_32x32x16_bf16 v[0:15], v[168:171], v[164:167], v[0:15]
	s_cbranch_vccnz .LBB0_297
	v_cndmask_b32_e64 v152, 0, 1, s[40:41]
	v_cmp_ne_u32_e64 s[38:39], 1, v152
	s_andn2_b64 vcc, exec, s[40:41]
	s_cbranch_vccz .LBB0_298
